# v24 + accumulator clearing with 64-bit moves (12 GEMM sites) + P0 compression-bias partial-sum loop pipelined
# speedup vs baseline: 1.0014x; 1.0014x over previous
.LBB0_696:
	s_ashr_i32 s19, s18, 31
	s_lshl_b64 s[20:21], s[18:19], 21
	s_add_u32 s20, s28, s20
	s_addc_u32 s21, s29, s21
	s_and_b64 s[22:23], s[2:3], exec
	s_cselect_b32 s19, s21, s25
	s_cselect_b32 s45, s20, s24
	s_ashr_i32 s17, s16, 31
	s_lshl_b64 s[22:23], s[16:17], 21
	s_add_u32 s22, s30, s22
	s_addc_u32 s23, s31, s23
	s_and_b64 s[26:27], s[2:3], exec
	s_cselect_b32 s17, s23, s5
	s_cselect_b32 s46, s22, s4
	s_add_u32 s47, s4, 0x100
	s_addc_u32 s48, s5, 0
	s_add_u32 s4, s24, 0x100080
	v_mov_b32_e32 v0, 0
	s_addc_u32 s5, s25, 0
	s_mov_b32 s49, -2
	v_mov_b64_e32 v[0:1], 0
	v_mov_b64_e32 v[2:3], 0
	v_mov_b64_e32 v[4:5], 0
	v_mov_b64_e32 v[6:7], 0
	v_mov_b64_e32 v[8:9], 0
	v_mov_b64_e32 v[10:11], 0
	v_mov_b64_e32 v[12:13], 0
	v_mov_b64_e32 v[14:15], 0
	v_mov_b64_e32 v[16:17], 0
	v_mov_b64_e32 v[18:19], 0
	v_mov_b64_e32 v[20:21], 0
	v_mov_b64_e32 v[22:23], 0
	v_mov_b64_e32 v[24:25], 0
	v_mov_b64_e32 v[26:27], 0
	v_mov_b64_e32 v[28:29], 0
	v_mov_b64_e32 v[30:31], 0
	v_mov_b64_e32 v[32:33], 0
	v_mov_b64_e32 v[34:35], 0
	v_mov_b64_e32 v[36:37], 0
	v_mov_b64_e32 v[38:39], 0
	v_mov_b64_e32 v[40:41], 0
	v_mov_b64_e32 v[42:43], 0
	v_mov_b64_e32 v[44:45], 0
	v_mov_b64_e32 v[46:47], 0
	v_mov_b64_e32 v[48:49], 0
	v_mov_b64_e32 v[50:51], 0
	v_mov_b64_e32 v[52:53], 0
	v_mov_b64_e32 v[54:55], 0
	v_mov_b64_e32 v[56:57], 0
	v_mov_b64_e32 v[58:59], 0
	v_mov_b64_e32 v[60:61], 0
	v_mov_b64_e32 v[62:63], 0
	v_mov_b64_e32 v[64:65], 0
	v_mov_b64_e32 v[66:67], 0
	v_mov_b64_e32 v[68:69], 0
	v_mov_b64_e32 v[70:71], 0
	v_mov_b64_e32 v[72:73], 0
	v_mov_b64_e32 v[74:75], 0
	v_mov_b64_e32 v[76:77], 0
	v_mov_b64_e32 v[78:79], 0
	v_mov_b64_e32 v[80:81], 0
	v_mov_b64_e32 v[82:83], 0
	v_mov_b64_e32 v[84:85], 0
	v_mov_b64_e32 v[86:87], 0
	v_mov_b64_e32 v[88:89], 0
	v_mov_b64_e32 v[90:91], 0
	v_mov_b64_e32 v[92:93], 0
	v_mov_b64_e32 v[94:95], 0
	v_mov_b64_e32 v[96:97], 0
	v_mov_b64_e32 v[98:99], 0
	v_mov_b64_e32 v[100:101], 0
	v_mov_b64_e32 v[102:103], 0
	v_mov_b64_e32 v[104:105], 0
	v_mov_b64_e32 v[106:107], 0
	v_mov_b64_e32 v[108:109], 0
	v_mov_b64_e32 v[110:111], 0
	v_mov_b64_e32 v[112:113], 0
	v_mov_b64_e32 v[114:115], 0
	v_mov_b64_e32 v[116:117], 0
	v_mov_b64_e32 v[118:119], 0
	v_mov_b64_e32 v[120:121], 0
	v_mov_b64_e32 v[122:123], 0
	v_mov_b64_e32 v[124:125], 0
	v_mov_b64_e32 v[126:127], 0

.LBB0_834:
	s_ashr_i32 s13, s12, 31
	s_lshl_b64 s[18:19], s[12:13], 21
	s_add_u32 s18, s28, s18
	s_addc_u32 s19, s29, s19
	s_and_b64 s[24:25], s[24:25], exec
	s_cselect_b32 s13, s19, s21
	s_cselect_b32 s15, s18, s20
	s_add_u32 s44, s20, 0x100
	s_addc_u32 s45, s21, 0
	s_add_u32 s20, s22, 0x80080
	v_mov_b32_e32 v0, 0
	s_addc_u32 s21, s23, 0
	s_mov_b32 s46, -2
	v_mov_b64_e32 v[0:1], 0
	v_mov_b64_e32 v[2:3], 0
	v_mov_b64_e32 v[4:5], 0
	v_mov_b64_e32 v[6:7], 0
	v_mov_b64_e32 v[8:9], 0
	v_mov_b64_e32 v[10:11], 0
	v_mov_b64_e32 v[12:13], 0
	v_mov_b64_e32 v[14:15], 0
	v_mov_b64_e32 v[16:17], 0
	v_mov_b64_e32 v[18:19], 0
	v_mov_b64_e32 v[20:21], 0
	v_mov_b64_e32 v[22:23], 0
	v_mov_b64_e32 v[24:25], 0
	v_mov_b64_e32 v[26:27], 0
	v_mov_b64_e32 v[28:29], 0
	v_mov_b64_e32 v[30:31], 0
	v_mov_b64_e32 v[40:41], 0
	v_mov_b64_e32 v[42:43], 0
	v_mov_b64_e32 v[44:45], 0
	v_mov_b64_e32 v[46:47], 0
	v_mov_b64_e32 v[56:57], 0
	v_mov_b64_e32 v[58:59], 0
	v_mov_b64_e32 v[60:61], 0
	v_mov_b64_e32 v[62:63], 0
	v_mov_b64_e32 v[64:65], 0
	v_mov_b64_e32 v[66:67], 0
	v_mov_b64_e32 v[68:69], 0
	v_mov_b64_e32 v[70:71], 0
	v_mov_b64_e32 v[72:73], 0
	v_mov_b64_e32 v[74:75], 0
	v_mov_b64_e32 v[76:77], 0
	v_mov_b64_e32 v[78:79], 0
	v_mov_b64_e32 v[80:81], 0
	v_mov_b64_e32 v[82:83], 0
	v_mov_b64_e32 v[84:85], 0
	v_mov_b64_e32 v[86:87], 0
	v_mov_b64_e32 v[88:89], 0
	v_mov_b64_e32 v[90:91], 0
	v_mov_b64_e32 v[92:93], 0
	v_mov_b64_e32 v[94:95], 0
	v_mov_b64_e32 v[96:97], 0
	v_mov_b64_e32 v[98:99], 0
	v_mov_b64_e32 v[100:101], 0
	v_mov_b64_e32 v[102:103], 0
	v_mov_b64_e32 v[104:105], 0
	v_mov_b64_e32 v[106:107], 0
	v_mov_b64_e32 v[108:109], 0
	v_mov_b64_e32 v[110:111], 0
	v_mov_b64_e32 v[112:113], 0
	v_mov_b64_e32 v[114:115], 0
	v_mov_b64_e32 v[116:117], 0
	v_mov_b64_e32 v[118:119], 0
	v_mov_b64_e32 v[120:121], 0
	v_mov_b64_e32 v[122:123], 0
	v_mov_b64_e32 v[124:125], 0
	v_mov_b64_e32 v[126:127], 0
	v_mov_b64_e32 v[128:129], 0
	v_mov_b64_e32 v[130:131], 0
	v_mov_b64_e32 v[132:133], 0
	v_mov_b64_e32 v[134:135], 0
	v_mov_b64_e32 v[136:137], 0
	v_mov_b64_e32 v[138:139], 0
	v_mov_b64_e32 v[140:141], 0
	v_mov_b64_e32 v[142:143], 0

.LBB0_855:
	s_ashr_i32 s19, s18, 31
	s_lshl_b64 s[20:21], s[18:19], 21
	s_add_u32 s20, s30, s20
	s_addc_u32 s21, s31, s21
	s_and_b64 s[22:23], s[14:15], exec
	s_cselect_b32 s19, s21, s25
	s_cselect_b32 s46, s20, s24
	s_ashr_i32 s17, s16, 31
	s_lshl_b64 s[22:23], s[16:17], 21
	s_add_u32 s22, s2, s22
	s_addc_u32 s23, s3, s23
	s_and_b64 s[28:29], s[14:15], exec
	s_cselect_b32 s17, s23, s27
	s_cselect_b32 s47, s22, s26
	s_add_u32 s48, s26, 0x100
	s_addc_u32 s49, s27, 0
	s_add_u32 s24, s24, 0x100080
	v_mov_b32_e32 v0, 0
	s_addc_u32 s25, s25, 0
	s_mov_b32 s50, -2
	v_mov_b64_e32 v[0:1], 0
	v_mov_b64_e32 v[2:3], 0
	v_mov_b64_e32 v[4:5], 0
	v_mov_b64_e32 v[6:7], 0
	v_mov_b64_e32 v[8:9], 0
	v_mov_b64_e32 v[10:11], 0
	v_mov_b64_e32 v[12:13], 0
	v_mov_b64_e32 v[14:15], 0
	v_mov_b64_e32 v[16:17], 0
	v_mov_b64_e32 v[18:19], 0
	v_mov_b64_e32 v[20:21], 0
	v_mov_b64_e32 v[22:23], 0
	v_mov_b64_e32 v[24:25], 0
	v_mov_b64_e32 v[26:27], 0
	v_mov_b64_e32 v[28:29], 0
	v_mov_b64_e32 v[30:31], 0
	v_mov_b64_e32 v[32:33], 0
	v_mov_b64_e32 v[34:35], 0
	v_mov_b64_e32 v[36:37], 0
	v_mov_b64_e32 v[38:39], 0
	v_mov_b64_e32 v[40:41], 0
	v_mov_b64_e32 v[42:43], 0
	v_mov_b64_e32 v[44:45], 0
	v_mov_b64_e32 v[46:47], 0
	v_mov_b64_e32 v[48:49], 0
	v_mov_b64_e32 v[50:51], 0
	v_mov_b64_e32 v[52:53], 0
	v_mov_b64_e32 v[54:55], 0
	v_mov_b64_e32 v[56:57], 0
	v_mov_b64_e32 v[58:59], 0
	v_mov_b64_e32 v[60:61], 0
	v_mov_b64_e32 v[62:63], 0

.LBB0_981:
	s_ashr_i32 s11, s10, 31
	s_ashr_i32 s9, s8, 31
	s_lshl_b64 s[12:13], s[8:9], 22
	s_lshl_b64 s[14:15], s[10:11], 18
	s_add_u32 s11, s24, s14
	s_addc_u32 s14, s25, s15
	s_add_u32 s12, s11, s12
	s_addc_u32 s13, s14, s13
	s_and_b64 s[14:15], s[6:7], exec
	s_cselect_b32 s11, s13, s21
	s_cselect_b32 s33, s12, s20
	s_lshl_b64 s[14:15], s[8:9], 18
	s_add_u32 s14, s26, s14
	s_addc_u32 s15, s27, s15
	s_and_b64 s[22:23], s[6:7], exec
	s_cselect_b32 s9, s15, s19
	s_cselect_b32 s44, s14, s18
	s_add_u32 s45, s18, 0x100
	s_addc_u32 s46, s19, 0
	s_add_u32 s18, s20, 0x20080
	v_mov_b32_e32 v0, 0
	s_addc_u32 s19, s21, 0
	s_mov_b32 s47, -2
	v_mov_b64_e32 v[0:1], 0
	v_mov_b64_e32 v[2:3], 0
	v_mov_b64_e32 v[4:5], 0
	v_mov_b64_e32 v[6:7], 0
	v_mov_b64_e32 v[8:9], 0
	v_mov_b64_e32 v[10:11], 0
	v_mov_b64_e32 v[12:13], 0
	v_mov_b64_e32 v[14:15], 0
	v_mov_b64_e32 v[16:17], 0
	v_mov_b64_e32 v[18:19], 0
	v_mov_b64_e32 v[20:21], 0
	v_mov_b64_e32 v[22:23], 0
	v_mov_b64_e32 v[24:25], 0
	v_mov_b64_e32 v[26:27], 0
	v_mov_b64_e32 v[28:29], 0
	v_mov_b64_e32 v[30:31], 0
	v_mov_b64_e32 v[32:33], 0
	v_mov_b64_e32 v[34:35], 0
	v_mov_b64_e32 v[36:37], 0
	v_mov_b64_e32 v[38:39], 0
	v_mov_b64_e32 v[40:41], 0
	v_mov_b64_e32 v[42:43], 0
	v_mov_b64_e32 v[44:45], 0
	v_mov_b64_e32 v[46:47], 0
	v_mov_b64_e32 v[48:49], 0
	v_mov_b64_e32 v[50:51], 0
	v_mov_b64_e32 v[52:53], 0
	v_mov_b64_e32 v[54:55], 0
	v_mov_b64_e32 v[56:57], 0
	v_mov_b64_e32 v[58:59], 0
	v_mov_b64_e32 v[60:61], 0
	v_mov_b64_e32 v[62:63], 0

.LBB0_1508:
	s_ashr_i32 s17, s16, 31
	s_lshl_b64 s[20:21], s[16:17], 21
	s_add_u32 s20, s30, s20
	s_addc_u32 s21, s31, s21
	s_and_b64 s[22:23], s[4:5], exec
	s_cselect_b32 s17, s21, s27
	s_cselect_b32 s47, s20, s26
	s_ashr_i32 s19, s18, 31
	s_lshl_b64 s[22:23], s[18:19], 21
	s_add_u32 s22, s34, s22
	s_addc_u32 s23, s35, s23
	s_and_b64 s[28:29], s[4:5], exec
	s_cselect_b32 s19, s23, s25
	s_cselect_b32 s48, s22, s24
	s_add_u32 s49, s24, 0x100
	s_addc_u32 s50, s25, 0
	s_add_u32 s24, s26, 0x100080
	v_mov_b32_e32 v0, 0
	s_addc_u32 s25, s27, 0
	s_mov_b32 s51, -2
	v_mov_b64_e32 v[0:1], 0
	v_mov_b64_e32 v[2:3], 0
	v_mov_b64_e32 v[4:5], 0
	v_mov_b64_e32 v[6:7], 0
	v_mov_b64_e32 v[8:9], 0
	v_mov_b64_e32 v[10:11], 0
	v_mov_b64_e32 v[12:13], 0
	v_mov_b64_e32 v[14:15], 0
	v_mov_b64_e32 v[16:17], 0
	v_mov_b64_e32 v[18:19], 0
	v_mov_b64_e32 v[20:21], 0
	v_mov_b64_e32 v[22:23], 0
	v_mov_b64_e32 v[24:25], 0
	v_mov_b64_e32 v[26:27], 0
	v_mov_b64_e32 v[28:29], 0
	v_mov_b64_e32 v[30:31], 0
	v_mov_b64_e32 v[32:33], 0
	v_mov_b64_e32 v[34:35], 0
	v_mov_b64_e32 v[36:37], 0
	v_mov_b64_e32 v[38:39], 0
	v_mov_b64_e32 v[40:41], 0
	v_mov_b64_e32 v[42:43], 0
	v_mov_b64_e32 v[44:45], 0
	v_mov_b64_e32 v[46:47], 0
	v_mov_b64_e32 v[48:49], 0
	v_mov_b64_e32 v[50:51], 0
	v_mov_b64_e32 v[52:53], 0
	v_mov_b64_e32 v[54:55], 0
	v_mov_b64_e32 v[56:57], 0
	v_mov_b64_e32 v[58:59], 0
	v_mov_b64_e32 v[60:61], 0
	v_mov_b64_e32 v[62:63], 0
	v_mov_b64_e32 v[64:65], 0
	v_mov_b64_e32 v[66:67], 0
	v_mov_b64_e32 v[68:69], 0
	v_mov_b64_e32 v[70:71], 0
	v_mov_b64_e32 v[72:73], 0
	v_mov_b64_e32 v[74:75], 0
	v_mov_b64_e32 v[76:77], 0
	v_mov_b64_e32 v[78:79], 0
	v_mov_b64_e32 v[80:81], 0
	v_mov_b64_e32 v[82:83], 0
	v_mov_b64_e32 v[84:85], 0
	v_mov_b64_e32 v[86:87], 0
	v_mov_b64_e32 v[88:89], 0
	v_mov_b64_e32 v[90:91], 0
	v_mov_b64_e32 v[92:93], 0
	v_mov_b64_e32 v[94:95], 0
	v_mov_b64_e32 v[96:97], 0
	v_mov_b64_e32 v[98:99], 0
	v_mov_b64_e32 v[100:101], 0
	v_mov_b64_e32 v[102:103], 0
	v_mov_b64_e32 v[104:105], 0
	v_mov_b64_e32 v[106:107], 0
	v_mov_b64_e32 v[108:109], 0
	v_mov_b64_e32 v[110:111], 0
	v_mov_b64_e32 v[112:113], 0
	v_mov_b64_e32 v[114:115], 0
	v_mov_b64_e32 v[116:117], 0
	v_mov_b64_e32 v[118:119], 0
	v_mov_b64_e32 v[120:121], 0
	v_mov_b64_e32 v[122:123], 0
	v_mov_b64_e32 v[124:125], 0
	v_mov_b64_e32 v[126:127], 0

.LBB0_1593:
	s_ashr_i32 s21, s20, 31
	s_lshl_b64 s[24:25], s[20:21], 19
	s_add_u32 s24, s34, s24
	s_addc_u32 s25, s35, s25
	s_and_b64 s[6:7], s[6:7], exec
	s_cselect_b32 s19, s25, s27
	s_cselect_b32 s21, s24, s26
	s_add_u32 s47, s26, 0x100
	s_addc_u32 s48, s27, 0
	s_add_u32 s6, s28, 0x100080
	v_mov_b32_e32 v0, 0
	s_addc_u32 s7, s29, 0
	s_mov_b32 s49, -2
	v_mov_b64_e32 v[0:1], 0
	v_mov_b64_e32 v[2:3], 0
	v_mov_b64_e32 v[4:5], 0
	v_mov_b64_e32 v[6:7], 0
	v_mov_b64_e32 v[8:9], 0
	v_mov_b64_e32 v[10:11], 0
	v_mov_b64_e32 v[12:13], 0
	v_mov_b64_e32 v[14:15], 0
	v_mov_b64_e32 v[16:17], 0
	v_mov_b64_e32 v[18:19], 0
	v_mov_b64_e32 v[20:21], 0
	v_mov_b64_e32 v[22:23], 0
	v_mov_b64_e32 v[24:25], 0
	v_mov_b64_e32 v[26:27], 0
	v_mov_b64_e32 v[28:29], 0
	v_mov_b64_e32 v[30:31], 0
	v_mov_b64_e32 v[32:33], 0
	v_mov_b64_e32 v[34:35], 0
	v_mov_b64_e32 v[36:37], 0
	v_mov_b64_e32 v[38:39], 0
	v_mov_b64_e32 v[40:41], 0
	v_mov_b64_e32 v[42:43], 0
	v_mov_b64_e32 v[44:45], 0
	v_mov_b64_e32 v[46:47], 0
	v_mov_b64_e32 v[48:49], 0
	v_mov_b64_e32 v[50:51], 0
	v_mov_b64_e32 v[52:53], 0
	v_mov_b64_e32 v[54:55], 0
	v_mov_b64_e32 v[56:57], 0
	v_mov_b64_e32 v[58:59], 0
	v_mov_b64_e32 v[60:61], 0
	v_mov_b64_e32 v[62:63], 0
	v_mov_b64_e32 v[64:65], 0
	v_mov_b64_e32 v[66:67], 0
	v_mov_b64_e32 v[68:69], 0
	v_mov_b64_e32 v[70:71], 0
	v_mov_b64_e32 v[72:73], 0
	v_mov_b64_e32 v[74:75], 0
	v_mov_b64_e32 v[76:77], 0
	v_mov_b64_e32 v[78:79], 0
	v_mov_b64_e32 v[80:81], 0
	v_mov_b64_e32 v[82:83], 0
	v_mov_b64_e32 v[84:85], 0
	v_mov_b64_e32 v[86:87], 0
	v_mov_b64_e32 v[88:89], 0
	v_mov_b64_e32 v[90:91], 0
	v_mov_b64_e32 v[92:93], 0
	v_mov_b64_e32 v[94:95], 0
	v_mov_b64_e32 v[96:97], 0
	v_mov_b64_e32 v[98:99], 0
	v_mov_b64_e32 v[100:101], 0
	v_mov_b64_e32 v[102:103], 0
	v_mov_b64_e32 v[104:105], 0
	v_mov_b64_e32 v[106:107], 0
	v_mov_b64_e32 v[108:109], 0
	v_mov_b64_e32 v[110:111], 0
	v_mov_b64_e32 v[128:129], 0
	v_mov_b64_e32 v[130:131], 0
	v_mov_b64_e32 v[132:133], 0
	v_mov_b64_e32 v[134:135], 0
	v_mov_b64_e32 v[136:137], 0
	v_mov_b64_e32 v[138:139], 0
	v_mov_b64_e32 v[140:141], 0
	v_mov_b64_e32 v[142:143], 0

.LBB0_1757:
	s_ashr_i32 s19, s18, 31
	s_lshl_b64 s[20:21], s[18:19], 21
	s_add_u32 s20, s30, s20
	s_addc_u32 s21, s31, s21
	s_and_b64 s[22:23], s[2:3], exec
	s_cselect_b32 s19, s21, s27
	s_cselect_b32 s46, s20, s26
	s_ashr_i32 s17, s16, 31
	s_lshl_b64 s[22:23], s[16:17], 21
	s_add_u32 s22, s34, s22
	s_addc_u32 s23, s35, s23
	s_and_b64 s[28:29], s[2:3], exec
	s_cselect_b32 s17, s23, s25
	s_cselect_b32 s47, s22, s24
	s_add_u32 s48, s24, 0x100
	s_addc_u32 s49, s25, 0
	s_add_u32 s24, s26, 0x100080
	v_mov_b32_e32 v0, 0
	s_addc_u32 s25, s27, 0
	s_mov_b32 s50, -2
	v_mov_b64_e32 v[0:1], 0
	v_mov_b64_e32 v[2:3], 0
	v_mov_b64_e32 v[4:5], 0
	v_mov_b64_e32 v[6:7], 0
	v_mov_b64_e32 v[8:9], 0
	v_mov_b64_e32 v[10:11], 0
	v_mov_b64_e32 v[12:13], 0
	v_mov_b64_e32 v[14:15], 0
	v_mov_b64_e32 v[16:17], 0
	v_mov_b64_e32 v[18:19], 0
	v_mov_b64_e32 v[20:21], 0
	v_mov_b64_e32 v[22:23], 0
	v_mov_b64_e32 v[24:25], 0
	v_mov_b64_e32 v[26:27], 0
	v_mov_b64_e32 v[28:29], 0
	v_mov_b64_e32 v[30:31], 0
	v_mov_b64_e32 v[32:33], 0
	v_mov_b64_e32 v[34:35], 0
	v_mov_b64_e32 v[36:37], 0
	v_mov_b64_e32 v[38:39], 0
	v_mov_b64_e32 v[40:41], 0
	v_mov_b64_e32 v[42:43], 0
	v_mov_b64_e32 v[44:45], 0
	v_mov_b64_e32 v[46:47], 0
	v_mov_b64_e32 v[48:49], 0
	v_mov_b64_e32 v[50:51], 0
	v_mov_b64_e32 v[52:53], 0
	v_mov_b64_e32 v[54:55], 0
	v_mov_b64_e32 v[56:57], 0
	v_mov_b64_e32 v[58:59], 0
	v_mov_b64_e32 v[60:61], 0
	v_mov_b64_e32 v[62:63], 0
	v_mov_b64_e32 v[64:65], 0
	v_mov_b64_e32 v[66:67], 0
	v_mov_b64_e32 v[68:69], 0
	v_mov_b64_e32 v[70:71], 0
	v_mov_b64_e32 v[72:73], 0
	v_mov_b64_e32 v[74:75], 0
	v_mov_b64_e32 v[76:77], 0
	v_mov_b64_e32 v[78:79], 0
	v_mov_b64_e32 v[80:81], 0
	v_mov_b64_e32 v[82:83], 0
	v_mov_b64_e32 v[84:85], 0
	v_mov_b64_e32 v[86:87], 0
	v_mov_b64_e32 v[88:89], 0
	v_mov_b64_e32 v[90:91], 0
	v_mov_b64_e32 v[92:93], 0
	v_mov_b64_e32 v[94:95], 0
	v_mov_b64_e32 v[96:97], 0
	v_mov_b64_e32 v[98:99], 0
	v_mov_b64_e32 v[100:101], 0
	v_mov_b64_e32 v[102:103], 0
	v_mov_b64_e32 v[104:105], 0
	v_mov_b64_e32 v[106:107], 0
	v_mov_b64_e32 v[108:109], 0
	v_mov_b64_e32 v[110:111], 0
	v_mov_b64_e32 v[112:113], 0
	v_mov_b64_e32 v[114:115], 0
	v_mov_b64_e32 v[116:117], 0
	v_mov_b64_e32 v[118:119], 0
	v_mov_b64_e32 v[120:121], 0
	v_mov_b64_e32 v[122:123], 0
	v_mov_b64_e32 v[124:125], 0
	v_mov_b64_e32 v[126:127], 0

.LBB0_1770:
	v_lshrrev_b32_e32 v16, 1, v12
	v_and_b32_e32 v75, 24, v16
	s_lshl_b32 s8, s8, 5
	v_and_b32_e32 v15, 15, v12
	v_lshlrev_b32_e32 v16, 1, v75
	v_lshlrev_b32_e32 v12, 2, v12
	s_and_b32 s22, s8, 0x60
	s_add_i32 m0, s18, 0x18000
	v_lshl_add_u64 v[6:7], v[6:7], 0, s[88:89]
	v_lshl_or_b32 v74, s9, 6, v15
	v_lshl_or_b32 v15, v15, 6, v16
	s_lshl_b32 s9, s9, 13
	v_and_b32_e32 v12, 32, v12
	s_lshl_b32 s8, s22, 7
	s_waitcnt vmcnt(2)
	s_barrier
	global_load_lds_dwordx4 v[6:7], off
	v_lshl_add_u64 v[4:5], v[4:5], 0, s[88:89]
	s_add_i32 m0, s18, 0x1a000
	s_add_i32 s23, s18, 0x8000
	s_add_i32 s24, s18, 0xa000
	v_bitop3_b32 v76, v15, s8, v12 bitop3:0xde
	global_load_lds_dwordx4 v[4:5], off
	v_lshl_add_u64 v[2:3], v[2:3], 0, s[88:89]
	s_mov_b32 m0, s23
	s_add_u32 s8, s2, 0x100080
	v_bitop3_b32 v16, v15, s9, v12 bitop3:0xde
	global_load_lds_dwordx4 v[2:3], off
	v_lshl_add_u64 v[0:1], v[0:1], 0, s[88:89]
	s_mov_b32 m0, s24
	s_addc_u32 s9, s3, 0
	global_load_lds_dwordx4 v[0:1], off
	s_add_i32 m0, s18, 0x1c000
	v_lshl_add_u64 v[0:1], s[8:9], 0, v[144:145]
	global_load_lds_dwordx4 v[0:1], off
	v_lshl_add_u64 v[0:1], s[8:9], 0, v[64:65]
	s_add_i32 m0, s18, 0x1e000
	v_readlane_b32 s8, v254, 27
	global_load_lds_dwordx4 v[0:1], off
	v_lshlrev_b32_e32 v0, 16, v8
	s_add_u32 s25, s4, s8
	v_and_b32_e32 v0, 0xfffe0000, v0
	s_addc_u32 s26, s5, 0
	v_readlane_b32 s8, v254, 30
	v_lshl_add_u32 v0, v9, 13, v0
	v_and_b32_e32 v1, 1, v8
	s_add_u32 s8, s4, s8
	v_readlane_b32 s9, v254, 31
	v_lshl_or_b32 v0, v1, 6, v0
	s_addc_u32 s9, s5, s9
	v_lshl_add_u32 v0, v10, 1, v0
	v_mov_b32_e32 v1, v145
	v_lshl_add_u64 v[70:71], s[8:9], 0, v[0:1]
	v_lshlrev_b32_e32 v0, 16, v13
	v_and_b32_e32 v0, 0xfffe0000, v0
	v_lshl_add_u32 v0, v11, 13, v0
	v_and_b32_e32 v1, 1, v13
	v_lshl_or_b32 v0, v1, 6, v0
	v_lshl_add_u32 v0, v14, 1, v0
	v_mov_b32_e32 v1, v145
	s_waitcnt vmcnt(6)
	v_lshl_add_u64 v[72:73], s[8:9], 0, v[0:1]
	v_readlane_b32 s8, v254, 29
	s_add_u32 s27, s4, s8
	v_mov_b32_e32 v0, 0
	s_addc_u32 s28, s5, 0
	s_mov_b32 s29, -2
	s_mov_b64 s[8:9], 0
	v_add_u32_e32 v77, 0, v16
	v_mov_b64_e32 v[0:1], 0
	v_mov_b64_e32 v[2:3], 0
	v_mov_b64_e32 v[4:5], 0
	v_mov_b64_e32 v[6:7], 0
	v_mov_b64_e32 v[8:9], 0
	v_mov_b64_e32 v[10:11], 0
	v_mov_b64_e32 v[12:13], 0
	v_mov_b64_e32 v[14:15], 0
	v_mov_b64_e32 v[16:17], 0
	v_mov_b64_e32 v[18:19], 0
	v_mov_b64_e32 v[20:21], 0
	v_mov_b64_e32 v[22:23], 0
	v_mov_b64_e32 v[24:25], 0
	v_mov_b64_e32 v[26:27], 0
	v_mov_b64_e32 v[28:29], 0
	v_mov_b64_e32 v[30:31], 0
	v_mov_b64_e32 v[32:33], 0
	v_mov_b64_e32 v[34:35], 0
	v_mov_b64_e32 v[36:37], 0
	v_mov_b64_e32 v[38:39], 0
	v_mov_b64_e32 v[40:41], 0
	v_mov_b64_e32 v[42:43], 0
	v_mov_b64_e32 v[44:45], 0
	v_mov_b64_e32 v[46:47], 0
	v_mov_b64_e32 v[48:49], 0
	v_mov_b64_e32 v[50:51], 0
	v_mov_b64_e32 v[52:53], 0
	v_mov_b64_e32 v[54:55], 0
	v_mov_b64_e32 v[56:57], 0
	v_mov_b64_e32 v[58:59], 0
	v_mov_b64_e32 v[60:61], 0
	v_mov_b64_e32 v[62:63], 0
	s_barrier

.LBB0_1789:
	s_ashr_i32 s15, s14, 31
	s_lshl_b64 s[16:17], s[14:15], 21
	s_add_u32 s16, s26, s16
	s_addc_u32 s17, s27, s17
	s_and_b64 s[18:19], s[8:9], exec
	s_cselect_b32 s15, s17, s23
	s_cselect_b32 s43, s16, s22
	s_ashr_i32 s13, s12, 31
	s_lshl_b64 s[18:19], s[12:13], 21
	s_add_u32 s18, s28, s18
	s_addc_u32 s19, s29, s19
	s_and_b64 s[24:25], s[8:9], exec
	s_cselect_b32 s13, s19, s21
	s_cselect_b32 s44, s18, s20
	s_add_u32 s45, s20, 0x100
	s_addc_u32 s46, s21, 0
	s_add_u32 s20, s22, 0x100080
	v_mov_b32_e32 v0, 0
	s_addc_u32 s21, s23, 0
	s_mov_b32 s47, -2
	v_mov_b64_e32 v[0:1], 0
	v_mov_b64_e32 v[2:3], 0
	v_mov_b64_e32 v[4:5], 0
	v_mov_b64_e32 v[6:7], 0
	v_mov_b64_e32 v[8:9], 0
	v_mov_b64_e32 v[10:11], 0
	v_mov_b64_e32 v[12:13], 0
	v_mov_b64_e32 v[14:15], 0
	v_mov_b64_e32 v[16:17], 0
	v_mov_b64_e32 v[18:19], 0
	v_mov_b64_e32 v[20:21], 0
	v_mov_b64_e32 v[22:23], 0
	v_mov_b64_e32 v[24:25], 0
	v_mov_b64_e32 v[26:27], 0
	v_mov_b64_e32 v[28:29], 0
	v_mov_b64_e32 v[30:31], 0
	v_mov_b64_e32 v[32:33], 0
	v_mov_b64_e32 v[34:35], 0
	v_mov_b64_e32 v[36:37], 0
	v_mov_b64_e32 v[38:39], 0
	v_mov_b64_e32 v[40:41], 0
	v_mov_b64_e32 v[42:43], 0
	v_mov_b64_e32 v[44:45], 0
	v_mov_b64_e32 v[46:47], 0
	v_mov_b64_e32 v[48:49], 0
	v_mov_b64_e32 v[50:51], 0
	v_mov_b64_e32 v[52:53], 0
	v_mov_b64_e32 v[54:55], 0
	v_mov_b64_e32 v[56:57], 0
	v_mov_b64_e32 v[58:59], 0
	v_mov_b64_e32 v[60:61], 0
	v_mov_b64_e32 v[62:63], 0
	v_mov_b64_e32 v[64:65], 0
	v_mov_b64_e32 v[66:67], 0
	v_mov_b64_e32 v[68:69], 0
	v_mov_b64_e32 v[70:71], 0
	v_mov_b64_e32 v[72:73], 0
	v_mov_b64_e32 v[74:75], 0
	v_mov_b64_e32 v[76:77], 0
	v_mov_b64_e32 v[78:79], 0
	v_mov_b64_e32 v[80:81], 0
	v_mov_b64_e32 v[82:83], 0
	v_mov_b64_e32 v[84:85], 0
	v_mov_b64_e32 v[86:87], 0
	v_mov_b64_e32 v[88:89], 0
	v_mov_b64_e32 v[90:91], 0
	v_mov_b64_e32 v[92:93], 0
	v_mov_b64_e32 v[94:95], 0
	v_mov_b64_e32 v[96:97], 0
	v_mov_b64_e32 v[98:99], 0
	v_mov_b64_e32 v[100:101], 0
	v_mov_b64_e32 v[102:103], 0
	v_mov_b64_e32 v[104:105], 0
	v_mov_b64_e32 v[106:107], 0
	v_mov_b64_e32 v[108:109], 0
	v_mov_b64_e32 v[110:111], 0
	v_mov_b64_e32 v[112:113], 0
	v_mov_b64_e32 v[114:115], 0
	v_mov_b64_e32 v[116:117], 0
	v_mov_b64_e32 v[118:119], 0
	v_mov_b64_e32 v[120:121], 0
	v_mov_b64_e32 v[122:123], 0
	v_mov_b64_e32 v[124:125], 0
	v_mov_b64_e32 v[126:127], 0

.LBB0_2005:
	s_ashr_i32 s19, s18, 31
	s_lshl_b64 s[22:23], s[18:19], 18
	s_add_u32 s22, s34, s22
	s_addc_u32 s23, s35, s23
	s_and_b64 s[24:25], s[6:7], exec
	s_cselect_b32 s19, s23, s29
	s_cselect_b32 s49, s22, s28
	s_ashr_i32 s21, s20, 31
	s_lshl_b64 s[24:25], s[20:21], 18
	s_add_u32 s24, s36, s24
	s_addc_u32 s25, s37, s25
	s_and_b64 s[30:31], s[6:7], exec
	s_cselect_b32 s21, s25, s27
	s_cselect_b32 s50, s24, s26
	s_add_u32 s51, s26, 0x100
	s_addc_u32 s52, s27, 0
	s_add_u32 s26, s28, 0x20080
	v_mov_b32_e32 v0, 0
	s_addc_u32 s27, s29, 0
	s_mov_b32 s53, -2
	v_mov_b64_e32 v[0:1], 0
	v_mov_b64_e32 v[2:3], 0
	v_mov_b64_e32 v[4:5], 0
	v_mov_b64_e32 v[6:7], 0
	v_mov_b64_e32 v[8:9], 0
	v_mov_b64_e32 v[10:11], 0
	v_mov_b64_e32 v[12:13], 0
	v_mov_b64_e32 v[14:15], 0
	v_mov_b64_e32 v[16:17], 0
	v_mov_b64_e32 v[18:19], 0
	v_mov_b64_e32 v[20:21], 0
	v_mov_b64_e32 v[22:23], 0
	v_mov_b64_e32 v[24:25], 0
	v_mov_b64_e32 v[26:27], 0
	v_mov_b64_e32 v[28:29], 0
	v_mov_b64_e32 v[30:31], 0
	v_mov_b64_e32 v[32:33], 0
	v_mov_b64_e32 v[34:35], 0
	v_mov_b64_e32 v[36:37], 0
	v_mov_b64_e32 v[38:39], 0
	v_mov_b64_e32 v[40:41], 0
	v_mov_b64_e32 v[42:43], 0
	v_mov_b64_e32 v[44:45], 0
	v_mov_b64_e32 v[46:47], 0
	v_mov_b64_e32 v[48:49], 0
	v_mov_b64_e32 v[50:51], 0
	v_mov_b64_e32 v[52:53], 0
	v_mov_b64_e32 v[54:55], 0
	v_mov_b64_e32 v[56:57], 0
	v_mov_b64_e32 v[58:59], 0
	v_mov_b64_e32 v[60:61], 0
	v_mov_b64_e32 v[62:63], 0
	v_mov_b64_e32 v[64:65], 0
	v_mov_b64_e32 v[66:67], 0
	v_mov_b64_e32 v[68:69], 0
	v_mov_b64_e32 v[70:71], 0
	v_mov_b64_e32 v[72:73], 0
	v_mov_b64_e32 v[74:75], 0
	v_mov_b64_e32 v[76:77], 0
	v_mov_b64_e32 v[78:79], 0
	v_mov_b64_e32 v[80:81], 0
	v_mov_b64_e32 v[82:83], 0
	v_mov_b64_e32 v[84:85], 0
	v_mov_b64_e32 v[86:87], 0
	v_mov_b64_e32 v[88:89], 0
	v_mov_b64_e32 v[90:91], 0
	v_mov_b64_e32 v[92:93], 0
	v_mov_b64_e32 v[94:95], 0
	v_mov_b64_e32 v[96:97], 0
	v_mov_b64_e32 v[98:99], 0
	v_mov_b64_e32 v[100:101], 0
	v_mov_b64_e32 v[102:103], 0
	v_mov_b64_e32 v[104:105], 0
	v_mov_b64_e32 v[106:107], 0
	v_mov_b64_e32 v[108:109], 0
	v_mov_b64_e32 v[110:111], 0
	v_mov_b64_e32 v[112:113], 0
	v_mov_b64_e32 v[114:115], 0
	v_mov_b64_e32 v[116:117], 0
	v_mov_b64_e32 v[118:119], 0
	v_mov_b64_e32 v[120:121], 0
	v_mov_b64_e32 v[122:123], 0
	v_mov_b64_e32 v[124:125], 0
	v_mov_b64_e32 v[126:127], 0

.LBB0_2146:
	s_ashr_i32 s51, s50, 31
	s_lshl_b64 s[52:53], s[50:51], 21
	s_add_u32 s52, s63, s52
	s_addc_u32 s53, s66, s53
	s_and_b64 s[54:55], s[8:9], exec
	s_cselect_b32 s51, s53, s59
	s_cselect_b32 s64, s52, s58
	s_ashr_i32 s49, s48, 31
	s_lshl_b64 s[54:55], s[48:49], 21
	s_add_u32 s54, s67, s54
	s_addc_u32 s55, s69, s55
	s_and_b64 s[60:61], s[8:9], exec
	s_cselect_b32 s49, s55, s57
	s_cselect_b32 s65, s54, s56
	s_add_u32 s95, s56, 0x100
	s_addc_u32 s97, s57, 0
	s_add_u32 s56, s58, 0x100080
	v_mov_b32_e32 v8, 0
	s_addc_u32 s57, s59, 0
	s_mov_b32 vcc_lo, -2
	v_mov_b64_e32 v[0:1], 0
	v_mov_b64_e32 v[2:3], 0
	v_mov_b64_e32 v[4:5], 0
	v_mov_b64_e32 v[6:7], 0
	v_mov_b64_e32 v[8:9], 0
	v_mov_b64_e32 v[10:11], 0
	v_mov_b64_e32 v[12:13], 0
	v_mov_b64_e32 v[14:15], 0
	v_mov_b64_e32 v[16:17], 0
	v_mov_b64_e32 v[18:19], 0
	v_mov_b64_e32 v[20:21], 0
	v_mov_b64_e32 v[22:23], 0
	v_mov_b64_e32 v[24:25], 0
	v_mov_b64_e32 v[26:27], 0
	v_mov_b64_e32 v[28:29], 0
	v_mov_b64_e32 v[30:31], 0
	v_mov_b64_e32 v[32:33], 0
	v_mov_b64_e32 v[34:35], 0
	v_mov_b64_e32 v[36:37], 0
	v_mov_b64_e32 v[38:39], 0
	v_mov_b64_e32 v[40:41], 0
	v_mov_b64_e32 v[42:43], 0
	v_mov_b64_e32 v[44:45], 0
	v_mov_b64_e32 v[46:47], 0
	v_mov_b64_e32 v[48:49], 0
	v_mov_b64_e32 v[50:51], 0
	v_mov_b64_e32 v[52:53], 0
	v_mov_b64_e32 v[54:55], 0
	v_mov_b64_e32 v[56:57], 0
	v_mov_b64_e32 v[58:59], 0
	v_mov_b64_e32 v[60:61], 0
	v_mov_b64_e32 v[62:63], 0
	v_mov_b64_e32 v[64:65], 0
	v_mov_b64_e32 v[66:67], 0
	v_mov_b64_e32 v[68:69], 0
	v_mov_b64_e32 v[70:71], 0
	v_mov_b64_e32 v[96:97], 0
	v_mov_b64_e32 v[98:99], 0
	v_mov_b64_e32 v[100:101], 0
	v_mov_b64_e32 v[102:103], 0
	v_mov_b64_e32 v[104:105], 0
	v_mov_b64_e32 v[106:107], 0
	v_mov_b64_e32 v[108:109], 0
	v_mov_b64_e32 v[110:111], 0
	v_mov_b64_e32 v[112:113], 0
	v_mov_b64_e32 v[114:115], 0
	v_mov_b64_e32 v[116:117], 0
	v_mov_b64_e32 v[118:119], 0
	v_mov_b64_e32 v[120:121], 0
	v_mov_b64_e32 v[122:123], 0
	v_mov_b64_e32 v[124:125], 0
	v_mov_b64_e32 v[126:127], 0
	v_mov_b64_e32 v[128:129], 0
	v_mov_b64_e32 v[130:131], 0
	v_mov_b64_e32 v[132:133], 0
	v_mov_b64_e32 v[134:135], 0
	v_mov_b64_e32 v[136:137], 0
	v_mov_b64_e32 v[138:139], 0
	v_mov_b64_e32 v[140:141], 0
	v_mov_b64_e32 v[142:143], 0
	v_mov_b64_e32 v[146:147], 0
	v_mov_b64_e32 v[148:149], 0
	v_mov_b64_e32 v[150:151], 0
	v_mov_b64_e32 v[152:153], 0
	v_add_u32_e32 v244, 0x10000, v207

.LBB0_2353:
	s_add_u32 s47, s22, 0x100
	v_mov_b32_e32 v0, 0
	s_addc_u32 s48, s23, 0
	s_mov_b32 s49, -2
	v_mov_b64_e32 v[0:1], 0
	v_mov_b64_e32 v[2:3], 0
	v_mov_b64_e32 v[4:5], 0
	v_mov_b64_e32 v[6:7], 0
	v_mov_b64_e32 v[8:9], 0
	v_mov_b64_e32 v[10:11], 0
	v_mov_b64_e32 v[12:13], 0
	v_mov_b64_e32 v[14:15], 0
	v_mov_b64_e32 v[16:17], 0
	v_mov_b64_e32 v[18:19], 0
	v_mov_b64_e32 v[20:21], 0
	v_mov_b64_e32 v[22:23], 0
	v_mov_b64_e32 v[24:25], 0
	v_mov_b64_e32 v[26:27], 0
	v_mov_b64_e32 v[28:29], 0
	v_mov_b64_e32 v[30:31], 0
	v_mov_b64_e32 v[32:33], 0
	v_mov_b64_e32 v[34:35], 0
	v_mov_b64_e32 v[36:37], 0
	v_mov_b64_e32 v[38:39], 0
	v_mov_b64_e32 v[40:41], 0
	v_mov_b64_e32 v[42:43], 0
	v_mov_b64_e32 v[44:45], 0
	v_mov_b64_e32 v[46:47], 0
	v_mov_b64_e32 v[48:49], 0
	v_mov_b64_e32 v[50:51], 0
	v_mov_b64_e32 v[52:53], 0
	v_mov_b64_e32 v[54:55], 0
	v_mov_b64_e32 v[56:57], 0
	v_mov_b64_e32 v[58:59], 0
	v_mov_b64_e32 v[60:61], 0
	v_mov_b64_e32 v[62:63], 0
	v_mov_b64_e32 v[64:65], 0
	v_mov_b64_e32 v[66:67], 0
	v_mov_b64_e32 v[68:69], 0
	v_mov_b64_e32 v[70:71], 0
	v_mov_b64_e32 v[72:73], 0
	v_mov_b64_e32 v[74:75], 0
	v_mov_b64_e32 v[76:77], 0
	v_mov_b64_e32 v[78:79], 0
	v_mov_b64_e32 v[80:81], 0
	v_mov_b64_e32 v[82:83], 0
	v_mov_b64_e32 v[84:85], 0
	v_mov_b64_e32 v[86:87], 0
	v_mov_b64_e32 v[88:89], 0
	v_mov_b64_e32 v[90:91], 0
	v_mov_b64_e32 v[92:93], 0
	v_mov_b64_e32 v[94:95], 0
	v_mov_b64_e32 v[96:97], 0
	v_mov_b64_e32 v[98:99], 0
	v_mov_b64_e32 v[100:101], 0
	v_mov_b64_e32 v[102:103], 0
	v_mov_b64_e32 v[104:105], 0
	v_mov_b64_e32 v[106:107], 0
	v_mov_b64_e32 v[108:109], 0
	v_mov_b64_e32 v[110:111], 0
	v_mov_b64_e32 v[112:113], 0
	v_mov_b64_e32 v[114:115], 0
	v_mov_b64_e32 v[116:117], 0
	v_mov_b64_e32 v[118:119], 0
	v_mov_b64_e32 v[120:121], 0
	v_mov_b64_e32 v[122:123], 0
	v_mov_b64_e32 v[124:125], 0
	v_mov_b64_e32 v[126:127], 0
	v_add_u32_e32 v244, 0x10000, v143
